# non-temporal hint on the P0 reads of x and the f32 weights (read once; keeps the infinity cache for proj / u / bf16 weights) and on the P3 base reads / h stores
# speedup vs baseline: 1.0529x; 1.0288x over previous
.LBB0_35:
	v_lshrrev_b32_e32 v53, 3, v52
	v_add_u32_e32 v3, v32, v53
	v_mad_i64_i32 v[6:7], s[22:23], s20, v3, 0
	v_cmp_lt_i32_e32 vcc, -1, v2
	v_mov_b32_e32 v4, 0
	v_mov_b32_e32 v3, v4
	v_cndmask_b32_e32 v2, 0, v2, vcc
	v_lshl_add_u64 v[0:1], v[6:7], 2, v[0:1]
	v_lshl_add_u64 v[36:37], v[2:3], 2, v[0:1]
	v_mov_b32_e32 v0, 0
	v_mov_b32_e32 v1, 0
	v_mov_b32_e32 v2, 0
	v_mov_b32_e32 v3, 0
	s_and_saveexec_b64 s[22:23], vcc
	s_cbranch_execz .LBB0_37
	global_load_dwordx4 v[0:3], v[36:37], off nt
.LBB0_37:
	s_or_b64 exec, exec, s[22:23]
	v_mov_b32_e32 v5, 0
	v_mov_b32_e32 v6, 0
	v_mov_b32_e32 v7, 0
	s_and_saveexec_b64 s[22:23], vcc
	s_cbranch_execz .LBB0_39
	s_lshl_b32 s24, s20, 5
	s_mov_b32 s25, 0
	v_lshl_add_u64 v[4:5], v[36:37], 0, s[24:25]
	global_load_dwordx4 v[4:7], v[4:5], off nt
.LBB0_39:
	s_or_b64 exec, exec, s[22:23]
	v_mov_b32_e32 v8, 0
	v_mov_b32_e32 v12, 0
	v_mov_b32_e32 v13, 0
	v_mov_b32_e32 v14, 0
	v_mov_b32_e32 v15, 0
	s_and_saveexec_b64 s[22:23], vcc
	s_cbranch_execz .LBB0_41
	s_lshl_b32 s24, s20, 6
	s_mov_b32 s25, 0
	v_lshl_add_u64 v[10:11], v[36:37], 0, s[24:25]
	global_load_dwordx4 v[12:15], v[10:11], off nt
.LBB0_41:
	s_or_b64 exec, exec, s[22:23]
	v_mov_b32_e32 v9, 0
	v_mov_b32_e32 v10, 0
	v_mov_b32_e32 v11, 0
	s_and_saveexec_b64 s[22:23], vcc
	s_cbranch_execz .LBB0_43
	v_mov_b32_e32 v8, 0x60
	v_mad_u64_u32 v[8:9], s[24:25], s20, v8, v[36:37]
	global_load_dwordx4 v[8:11], v[8:9], off nt
.LBB0_43:
	s_or_b64 exec, exec, s[22:23]
	v_mov_b32_e32 v16, 0
	v_mov_b32_e32 v20, 0
	v_mov_b32_e32 v21, 0
	v_mov_b32_e32 v22, 0
	v_mov_b32_e32 v23, 0
	s_and_saveexec_b64 s[22:23], vcc
	s_cbranch_execz .LBB0_45
	s_lshl_b32 s24, s20, 7
	s_mov_b32 s25, 0
	v_lshl_add_u64 v[18:19], v[36:37], 0, s[24:25]
	global_load_dwordx4 v[20:23], v[18:19], off nt
.LBB0_45:
	s_or_b64 exec, exec, s[22:23]
	v_mov_b32_e32 v17, 0
	v_mov_b32_e32 v18, 0
	v_mov_b32_e32 v19, 0
	s_and_saveexec_b64 s[22:23], vcc
	s_cbranch_execz .LBB0_47
	v_mov_b32_e32 v16, 0xa0
	v_mad_u64_u32 v[16:17], s[24:25], s20, v16, v[36:37]
	global_load_dwordx4 v[16:19], v[16:17], off nt
.LBB0_47:
	s_or_b64 exec, exec, s[22:23]
	v_mov_b32_e32 v24, 0
	v_mov_b32_e32 v28, 0
	v_mov_b32_e32 v29, 0
	v_mov_b32_e32 v30, 0
	v_mov_b32_e32 v31, 0
	s_and_saveexec_b64 s[22:23], vcc
	s_cbranch_execz .LBB0_49
	v_mov_b32_e32 v25, 0xc0
	v_mad_u64_u32 v[26:27], s[24:25], s20, v25, v[36:37]
	global_load_dwordx4 v[28:31], v[26:27], off nt
.LBB0_49:
	s_or_b64 exec, exec, s[22:23]
	v_mov_b32_e32 v25, 0
	v_mov_b32_e32 v26, 0
	v_mov_b32_e32 v27, 0
	s_and_saveexec_b64 s[22:23], vcc
	s_cbranch_execz .LBB0_51
	v_mov_b32_e32 v24, 0xe0
	v_mad_u64_u32 v[24:25], s[20:21], s20, v24, v[36:37]
	global_load_dwordx4 v[24:27], v[24:25], off nt

.LBB0_81:
	v_add_u32_e32 v3, v46, v53
	v_mad_i64_i32 v[4:5], s[24:25], s22, v3, 0
	v_cmp_lt_i32_e32 vcc, -1, v2
	v_lshl_add_u64 v[0:1], v[4:5], 2, v[0:1]
	v_mov_b32_e32 v4, 0
	v_cndmask_b32_e32 v32, 0, v2, vcc
	v_lshl_add_u64 v[50:51], v[32:33], 2, v[0:1]
	v_mov_b32_e32 v0, 0
	v_mov_b32_e32 v1, 0
	v_mov_b32_e32 v2, 0
	v_mov_b32_e32 v3, 0
	s_and_saveexec_b64 s[24:25], vcc
	s_cbranch_execz .LBB0_83
	global_load_dwordx4 v[0:3], v[50:51], off nt
.LBB0_83:
	s_or_b64 exec, exec, s[24:25]
	v_mov_b32_e32 v5, 0
	v_mov_b32_e32 v6, 0
	v_mov_b32_e32 v7, 0
	s_and_saveexec_b64 s[24:25], vcc
	s_cbranch_execz .LBB0_85
	s_lshl_b32 s18, s22, 5
	v_lshl_add_u64 v[4:5], v[50:51], 0, s[18:19]
	global_load_dwordx4 v[4:7], v[4:5], off nt
.LBB0_85:
	s_or_b64 exec, exec, s[24:25]
	v_mov_b32_e32 v8, 0
	v_mov_b32_e32 v12, 0
	v_mov_b32_e32 v13, 0
	v_mov_b32_e32 v14, 0
	v_mov_b32_e32 v15, 0
	s_and_saveexec_b64 s[24:25], vcc
	s_cbranch_execz .LBB0_87
	s_lshl_b32 s18, s22, 6
	v_lshl_add_u64 v[10:11], v[50:51], 0, s[18:19]
	global_load_dwordx4 v[12:15], v[10:11], off nt
.LBB0_87:
	s_or_b64 exec, exec, s[24:25]
	v_mov_b32_e32 v9, 0
	v_mov_b32_e32 v10, 0
	v_mov_b32_e32 v11, 0
	s_and_saveexec_b64 s[24:25], vcc
	s_cbranch_execz .LBB0_89
	v_mad_u64_u32 v[8:9], s[36:37], s22, v71, v[50:51]
	global_load_dwordx4 v[8:11], v[8:9], off nt
.LBB0_89:
	s_or_b64 exec, exec, s[24:25]
	v_mov_b32_e32 v16, 0
	v_mov_b32_e32 v20, 0
	v_mov_b32_e32 v21, 0
	v_mov_b32_e32 v22, 0
	v_mov_b32_e32 v23, 0
	s_and_saveexec_b64 s[24:25], vcc
	s_cbranch_execz .LBB0_91
	s_lshl_b32 s18, s22, 7
	v_lshl_add_u64 v[18:19], v[50:51], 0, s[18:19]
	global_load_dwordx4 v[20:23], v[18:19], off nt
.LBB0_91:
	s_or_b64 exec, exec, s[24:25]
	v_mov_b32_e32 v17, 0
	v_mov_b32_e32 v18, 0
	v_mov_b32_e32 v19, 0
	s_and_saveexec_b64 s[24:25], vcc
	s_cbranch_execz .LBB0_93
	v_mad_u64_u32 v[16:17], s[36:37], s22, v72, v[50:51]
	global_load_dwordx4 v[16:19], v[16:17], off nt
.LBB0_93:
	s_or_b64 exec, exec, s[24:25]
	v_mov_b32_e32 v24, 0
	v_mov_b32_e32 v28, 0
	v_mov_b32_e32 v29, 0
	v_mov_b32_e32 v30, 0
	v_mov_b32_e32 v31, 0
	s_and_saveexec_b64 s[24:25], vcc
	s_cbranch_execz .LBB0_95
	v_mad_u64_u32 v[26:27], s[36:37], s22, v73, v[50:51]
	global_load_dwordx4 v[28:31], v[26:27], off nt
.LBB0_95:
	s_or_b64 exec, exec, s[24:25]
	v_mov_b32_e32 v25, 0
	v_mov_b32_e32 v26, 0
	v_mov_b32_e32 v27, 0
	s_and_saveexec_b64 s[24:25], vcc
	s_cbranch_execz .LBB0_52
	v_mad_u64_u32 v[24:25], s[22:23], s22, v74, v[50:51]
	global_load_dwordx4 v[24:27], v[24:25], off nt
	s_branch .LBB0_52

.LBB0_99:
	s_add_i32 s2, s8, s0
	s_ashr_i32 s9, s8, 31
	s_ashr_i32 s3, s2, 31
	s_lshl_b64 s[4:5], s[8:9], 12
	v_lshl_add_u64 v[24:25], v[18:19], 0, s[4:5]
	s_lshl_b64 s[4:5], s[2:3], 12
	v_lshl_add_u64 v[66:67], v[18:19], 0, s[4:5]
	global_load_dwordx4 v[34:37], v[24:25], off nt
	global_load_dwordx4 v[38:41], v[24:25], off offset:1024 nt
	global_load_dwordx4 v[42:45], v[24:25], off offset:2048 nt
	global_load_dwordx4 v[46:49], v[24:25], off offset:3072 nt
	global_load_dwordx4 v[50:53], v[66:67], off offset:2048 nt
	global_load_dwordx4 v[54:57], v[66:67], off nt
	global_load_dwordx4 v[58:61], v[66:67], off offset:1024 nt
	global_load_dwordx4 v[62:65], v[66:67], off offset:3072 nt
	s_lshl_b64 s[10:11], s[8:9], 11
	s_add_i32 s8, s2, s0
	s_lshl_b64 s[2:3], s[2:3], 11
	v_lshl_add_u64 v[24:25], v[20:21], 0, s[2:3]
	v_lshl_add_u64 v[14:15], v[20:21], 0, s[10:11]
	s_cmpk_gt_i32 s8, 0x3fff
	s_waitcnt vmcnt(7)
	v_mov_b32_e32 v66, v34
	v_mov_b32_e32 v67, v36
	v_mov_b32_e32 v68, v35
	v_mov_b32_e32 v69, v37
	v_pk_mul_f32 v[36:37], v[36:37], v[36:37]
	v_pk_mul_f32 v[34:35], v[34:35], v[34:35]
	s_waitcnt vmcnt(6)
	v_mov_b32_e32 v70, v38
	v_mov_b32_e32 v71, v40
	v_mov_b32_e32 v72, v39
	v_mov_b32_e32 v73, v41
	v_pk_mul_f32 v[40:41], v[40:41], v[40:41]
	v_pk_mul_f32 v[38:39], v[38:39], v[38:39]
	s_waitcnt vmcnt(5)
	v_mul_f32_e32 v78, v43, v43
	v_mul_f32_e32 v80, v45, v45
	s_waitcnt vmcnt(3)
	v_mul_f32_e32 v86, v51, v51
	v_mov_b32_e32 v90, v34
	v_mov_b32_e32 v91, v36
	v_mov_b32_e32 v36, v35
	s_waitcnt vmcnt(2)
	v_mov_b32_e32 v34, v54
	v_mov_b32_e32 v35, v56
	v_mov_b32_e32 v92, v55
	v_mov_b32_e32 v93, v57
	v_pk_mul_f32 v[56:57], v[56:57], v[56:57]
	v_pk_mul_f32 v[54:55], v[54:55], v[54:55]
	v_mov_b32_e32 v94, v38
	v_mov_b32_e32 v95, v40
	v_mov_b32_e32 v40, v39
	s_waitcnt vmcnt(1)
	v_mov_b32_e32 v38, v58
	v_mov_b32_e32 v39, v60
	v_mov_b32_e32 v96, v59
	v_mov_b32_e32 v97, v61
	v_pk_mul_f32 v[60:61], v[60:61], v[60:61]
	v_pk_mul_f32 v[58:59], v[58:59], v[58:59]
	v_mov_b32_e32 v74, v42
	v_mov_b32_e32 v75, v44
	v_mov_b32_e32 v76, v43
	v_mov_b32_e32 v77, v45
	v_mov_b32_e32 v83, v48
	v_mov_b32_e32 v85, v49
	v_pk_mul_f32 v[48:49], v[48:49], v[48:49]
	v_pk_fma_f32 v[42:43], v[42:43], v[42:43], v[78:79] op_sel_hi:[1,1,0]
	v_pk_fma_f32 v[44:45], v[44:45], v[44:45], v[80:81] op_sel_hi:[1,1,0]
	v_mov_b32_e32 v78, v50
	v_mov_b32_e32 v80, v51
	v_pk_fma_f32 v[50:51], v[50:51], v[50:51], v[86:87] op_sel_hi:[1,1,0]
	v_mov_b32_e32 v86, v54
	v_mov_b32_e32 v87, v56
	v_mov_b32_e32 v56, v55
	v_mov_b32_e32 v54, v58
	v_mov_b32_e32 v55, v60
	v_mov_b32_e32 v60, v59
	v_mul_f32_e32 v88, v53, v53
	v_pk_add_f32 v[36:37], v[90:91], v[36:37]
	v_pk_add_f32 v[40:41], v[94:95], v[40:41]
	v_mov_b32_e32 v43, v48
	v_mov_b32_e32 v45, v49
	v_pk_add_f32 v[48:49], v[86:87], v[56:57]
	v_pk_add_f32 v[54:55], v[54:55], v[60:61]
	v_mov_b32_e32 v82, v46
	v_mov_b32_e32 v84, v47
	v_pk_mul_f32 v[46:47], v[46:47], v[46:47]
	v_mov_b32_e32 v79, v52
	v_mov_b32_e32 v81, v53
	s_waitcnt vmcnt(0)
	v_mov_b32_e32 v98, v62
	v_mov_b32_e32 v99, v64
	v_mov_b32_e32 v100, v63
	v_mov_b32_e32 v101, v65
	v_pk_mul_f32 v[64:65], v[64:65], v[64:65]
	v_pk_mul_f32 v[62:63], v[62:63], v[62:63]
	v_pk_fma_f32 v[52:53], v[52:53], v[52:53], v[88:89] op_sel_hi:[1,1,0]
	v_pk_add_f32 v[42:43], v[42:43], v[44:45]
	v_pk_add_f32 v[36:37], v[36:37], v[36:37] op_sel:[0,1] op_sel_hi:[1,0]
	v_pk_add_f32 v[40:41], v[40:41], v[40:41] op_sel:[0,1] op_sel_hi:[1,0]
	v_pk_add_f32 v[44:45], v[48:49], v[48:49] op_sel:[0,1] op_sel_hi:[1,0]
	v_pk_add_f32 v[48:49], v[54:55], v[54:55] op_sel:[0,1] op_sel_hi:[1,0]
	v_mov_b32_e32 v51, v64
	v_mov_b32_e32 v53, v65
	v_mov_b32_e32 v37, v46
	v_mov_b32_e32 v41, v47
	v_mov_b32_e32 v45, v62
	v_mov_b32_e32 v49, v63
	v_pk_add_f32 v[46:47], v[50:51], v[52:53]
	v_pk_add_f32 v[36:37], v[36:37], v[40:41]
	v_pk_add_f32 v[40:41], v[44:45], v[48:49]
	v_pk_add_f32 v[36:37], v[36:37], v[42:43]
	v_pk_add_f32 v[40:41], v[40:41], v[46:47]
	v_mov_b32_e32 v43, v36
	v_mov_b32_e32 v42, v40
	v_mov_b32_e32 v36, v41
	v_pk_add_f32 v[36:37], v[42:43], v[36:37]
	ds_bpermute_b32 v41, v26, v37
	ds_bpermute_b32 v40, v26, v36
	s_waitcnt lgkmcnt(0)
	v_pk_add_f32 v[36:37], v[36:37], v[40:41]
	ds_bpermute_b32 v41, v27, v37
	ds_bpermute_b32 v40, v27, v36
	s_waitcnt lgkmcnt(0)
	v_pk_add_f32 v[36:37], v[36:37], v[40:41]
	ds_bpermute_b32 v41, v28, v37
	ds_bpermute_b32 v40, v28, v36
	s_waitcnt lgkmcnt(0)
	v_pk_add_f32 v[36:37], v[36:37], v[40:41]
	ds_bpermute_b32 v41, v29, v37
	ds_bpermute_b32 v40, v29, v36
	s_waitcnt lgkmcnt(0)
	v_pk_add_f32 v[36:37], v[36:37], v[40:41]
	ds_bpermute_b32 v41, v30, v37
	ds_bpermute_b32 v40, v30, v36
	s_waitcnt lgkmcnt(0)
	v_pk_add_f32 v[36:37], v[36:37], v[40:41]
	ds_bpermute_b32 v41, v31, v37
	ds_bpermute_b32 v40, v31, v36
	s_waitcnt lgkmcnt(0)
	v_pk_add_f32 v[36:37], v[36:37], v[40:41]
	s_nop 0
	v_pk_fma_f32 v[36:37], v[36:37], s[6:7], v[16:17] op_sel_hi:[1,0,0]
	s_nop 0
	v_mul_f32_e32 v33, 0x4b800000, v37
	v_cmp_gt_f32_e64 s[2:3], s1, v37
	v_mul_f32_e32 v40, 0x4b800000, v36
	v_cmp_gt_f32_e32 vcc, s1, v36
	v_cndmask_b32_e64 v33, v37, v33, s[2:3]
	v_rsq_f32_e32 v33, v33
	v_cndmask_b32_e32 v36, v36, v40, vcc
	v_rsq_f32_e32 v37, v36
	v_mul_f32_e32 v36, 0x45800000, v33
	v_cndmask_b32_e64 v36, v33, v36, s[2:3]
	v_mul_f32_e32 v40, 0x45800000, v37
	v_cndmask_b32_e32 v40, v37, v40, vcc
	v_pk_mul_f32 v[42:43], v[66:67], v[36:37] op_sel_hi:[1,0]
	v_pk_mul_f32 v[44:45], v[68:69], v[36:37] op_sel_hi:[1,0]
	v_pk_mul_f32 v[46:47], v[70:71], v[36:37] op_sel_hi:[1,0]
	v_pk_mul_f32 v[48:49], v[72:73], v[36:37] op_sel_hi:[1,0]
	v_pk_mul_f32 v[50:51], v[74:75], v[36:37] op_sel_hi:[1,0]
	v_pk_mul_f32 v[52:53], v[76:77], v[36:37] op_sel_hi:[1,0]
	v_pk_mul_f32 v[54:55], v[82:83], v[36:37] op_sel_hi:[1,0]
	v_pk_mul_f32 v[36:37], v[84:85], v[36:37] op_sel_hi:[1,0]
	v_pk_mul_f32 v[34:35], v[34:35], v[40:41] op_sel_hi:[1,0]
	v_pk_mul_f32 v[56:57], v[92:93], v[40:41] op_sel_hi:[1,0]
	v_pk_mul_f32 v[38:39], v[38:39], v[40:41] op_sel_hi:[1,0]
	v_pk_mul_f32 v[58:59], v[96:97], v[40:41] op_sel_hi:[1,0]
	v_pk_mul_f32 v[60:61], v[78:79], v[40:41] op_sel_hi:[1,0]
	v_pk_mul_f32 v[62:63], v[80:81], v[40:41] op_sel_hi:[1,0]
	v_pk_mul_f32 v[64:65], v[98:99], v[40:41] op_sel_hi:[1,0]
	v_pk_mul_f32 v[40:41], v[100:101], v[40:41] op_sel_hi:[1,0]
	v_pk_mul_f32 v[42:43], v[0:1], v[42:43]
	v_pk_mul_f32 v[44:45], v[22:23], v[44:45]
	v_pk_mul_f32 v[46:47], v[4:5], v[46:47]
	v_pk_mul_f32 v[48:49], v[48:49], v[2:3]
	v_pk_mul_f32 v[50:51], v[50:51], v[8:9]
	v_pk_mul_f32 v[52:53], v[52:53], v[6:7]
	v_pk_mul_f32 v[54:55], v[54:55], v[12:13]
	v_pk_mul_f32 v[36:37], v[36:37], v[10:11]
	v_pk_mul_f32 v[34:35], v[0:1], v[34:35]
	v_pk_mul_f32 v[56:57], v[22:23], v[56:57]
	v_pk_mul_f32 v[38:39], v[4:5], v[38:39]
	v_pk_mul_f32 v[58:59], v[2:3], v[58:59]
	v_pk_mul_f32 v[60:61], v[60:61], v[8:9]
	v_pk_mul_f32 v[62:63], v[62:63], v[6:7]
	v_pk_mul_f32 v[40:41], v[40:41], v[10:11]
	v_and_b32_sdwa v33, v43, v32 dst_sel:DWORD dst_unused:UNUSED_PAD src0_sel:WORD_1 src1_sel:DWORD
	v_and_b32_sdwa v67, v45, v32 dst_sel:DWORD dst_unused:UNUSED_PAD src0_sel:WORD_1 src1_sel:DWORD
	v_and_b32_sdwa v68, v44, v32 dst_sel:DWORD dst_unused:UNUSED_PAD src0_sel:WORD_1 src1_sel:DWORD
	v_pk_mul_f32 v[64:65], v[64:65], v[12:13]
	v_and_b32_sdwa v66, v42, v32 dst_sel:DWORD dst_unused:UNUSED_PAD src0_sel:WORD_1 src1_sel:DWORD
	v_and_b32_sdwa v69, v47, v32 dst_sel:DWORD dst_unused:UNUSED_PAD src0_sel:WORD_1 src1_sel:DWORD
	v_and_b32_sdwa v70, v46, v32 dst_sel:DWORD dst_unused:UNUSED_PAD src0_sel:WORD_1 src1_sel:DWORD
	v_and_b32_sdwa v71, v49, v32 dst_sel:DWORD dst_unused:UNUSED_PAD src0_sel:WORD_1 src1_sel:DWORD
	v_and_b32_sdwa v72, v48, v32 dst_sel:DWORD dst_unused:UNUSED_PAD src0_sel:WORD_1 src1_sel:DWORD
	v_and_b32_sdwa v73, v51, v32 dst_sel:DWORD dst_unused:UNUSED_PAD src0_sel:WORD_1 src1_sel:DWORD
	v_and_b32_sdwa v74, v50, v32 dst_sel:DWORD dst_unused:UNUSED_PAD src0_sel:WORD_1 src1_sel:DWORD
	v_and_b32_sdwa v75, v53, v32 dst_sel:DWORD dst_unused:UNUSED_PAD src0_sel:WORD_1 src1_sel:DWORD
	v_and_b32_sdwa v76, v52, v32 dst_sel:DWORD dst_unused:UNUSED_PAD src0_sel:WORD_1 src1_sel:DWORD
	v_and_b32_sdwa v77, v55, v32 dst_sel:DWORD dst_unused:UNUSED_PAD src0_sel:WORD_1 src1_sel:DWORD
	v_and_b32_sdwa v78, v54, v32 dst_sel:DWORD dst_unused:UNUSED_PAD src0_sel:WORD_1 src1_sel:DWORD
	v_and_b32_sdwa v79, v37, v32 dst_sel:DWORD dst_unused:UNUSED_PAD src0_sel:WORD_1 src1_sel:DWORD
	v_and_b32_sdwa v80, v36, v32 dst_sel:DWORD dst_unused:UNUSED_PAD src0_sel:WORD_1 src1_sel:DWORD
	v_and_b32_sdwa v81, v35, v32 dst_sel:DWORD dst_unused:UNUSED_PAD src0_sel:WORD_1 src1_sel:DWORD
	v_and_b32_sdwa v82, v34, v32 dst_sel:DWORD dst_unused:UNUSED_PAD src0_sel:WORD_1 src1_sel:DWORD
	v_and_b32_sdwa v83, v57, v32 dst_sel:DWORD dst_unused:UNUSED_PAD src0_sel:WORD_1 src1_sel:DWORD
	v_and_b32_sdwa v84, v56, v32 dst_sel:DWORD dst_unused:UNUSED_PAD src0_sel:WORD_1 src1_sel:DWORD
	v_and_b32_sdwa v85, v39, v32 dst_sel:DWORD dst_unused:UNUSED_PAD src0_sel:WORD_1 src1_sel:DWORD
	v_and_b32_sdwa v86, v38, v32 dst_sel:DWORD dst_unused:UNUSED_PAD src0_sel:WORD_1 src1_sel:DWORD
	v_and_b32_sdwa v87, v59, v32 dst_sel:DWORD dst_unused:UNUSED_PAD src0_sel:WORD_1 src1_sel:DWORD
	v_and_b32_sdwa v88, v58, v32 dst_sel:DWORD dst_unused:UNUSED_PAD src0_sel:WORD_1 src1_sel:DWORD
	v_and_b32_sdwa v89, v61, v32 dst_sel:DWORD dst_unused:UNUSED_PAD src0_sel:WORD_1 src1_sel:DWORD
	v_and_b32_sdwa v90, v60, v32 dst_sel:DWORD dst_unused:UNUSED_PAD src0_sel:WORD_1 src1_sel:DWORD
	v_and_b32_sdwa v91, v63, v32 dst_sel:DWORD dst_unused:UNUSED_PAD src0_sel:WORD_1 src1_sel:DWORD
	v_and_b32_sdwa v92, v62, v32 dst_sel:DWORD dst_unused:UNUSED_PAD src0_sel:WORD_1 src1_sel:DWORD
	v_and_b32_sdwa v95, v41, v32 dst_sel:DWORD dst_unused:UNUSED_PAD src0_sel:WORD_1 src1_sel:DWORD
	v_and_b32_sdwa v96, v40, v32 dst_sel:DWORD dst_unused:UNUSED_PAD src0_sel:WORD_1 src1_sel:DWORD
	v_add3_u32 v33, v43, v33, s7
	v_add3_u32 v43, v45, v67, s7
	v_add3_u32 v44, v44, v68, s7
	v_and_b32_sdwa v93, v65, v32 dst_sel:DWORD dst_unused:UNUSED_PAD src0_sel:WORD_1 src1_sel:DWORD
	v_and_b32_sdwa v94, v64, v32 dst_sel:DWORD dst_unused:UNUSED_PAD src0_sel:WORD_1 src1_sel:DWORD
	v_add3_u32 v42, v42, v66, s7
	v_add3_u32 v45, v46, v70, s7
	v_add3_u32 v46, v47, v69, s7
	v_add3_u32 v47, v49, v71, s7
	v_add3_u32 v48, v48, v72, s7
	v_add3_u32 v49, v50, v74, s7
	v_add3_u32 v50, v51, v73, s7
	v_add3_u32 v51, v53, v75, s7
	v_add3_u32 v52, v52, v76, s7
	v_add3_u32 v53, v54, v78, s7
	v_add3_u32 v54, v55, v77, s7
	v_add3_u32 v37, v37, v79, s7
	v_add3_u32 v36, v36, v80, s7
	v_add3_u32 v55, v34, v82, s7
	v_add3_u32 v66, v35, v81, s7
	v_add3_u32 v34, v57, v83, s7
	v_add3_u32 v35, v56, v84, s7
	v_add3_u32 v56, v38, v86, s7
	v_add3_u32 v57, v39, v85, s7
	v_add3_u32 v38, v59, v87, s7
	v_add3_u32 v39, v58, v88, s7
	v_add3_u32 v58, v60, v90, s7
	v_add3_u32 v59, v61, v89, s7
	v_add3_u32 v60, v63, v91, s7
	v_add3_u32 v61, v62, v92, s7
	v_add3_u32 v41, v41, v95, s7
	v_add3_u32 v40, v40, v96, s7
	v_and_b32_e32 v43, 0xffff0000, v43
	v_and_b32_e32 v44, 0xffff0000, v44
	v_add3_u32 v62, v64, v94, s7
	v_add3_u32 v63, v65, v93, s7
	v_and_b32_e32 v47, 0xffff0000, v47
	v_and_b32_e32 v48, 0xffff0000, v48
	v_and_b32_e32 v51, 0xffff0000, v51
	v_and_b32_e32 v52, 0xffff0000, v52
	v_and_b32_e32 v64, 0xffff0000, v37
	v_and_b32_e32 v65, 0xffff0000, v36
	v_and_b32_e32 v67, 0xffff0000, v34
	v_and_b32_e32 v68, 0xffff0000, v35
	v_and_b32_e32 v69, 0xffff0000, v38
	v_and_b32_e32 v70, 0xffff0000, v39
	v_and_b32_e32 v60, 0xffff0000, v60
	v_and_b32_e32 v61, 0xffff0000, v61
	v_and_b32_e32 v71, 0xffff0000, v41
	v_and_b32_e32 v72, 0xffff0000, v40
	v_or_b32_sdwa v35, v43, v33 dst_sel:DWORD dst_unused:UNUSED_PAD src0_sel:DWORD src1_sel:WORD_1
	v_or_b32_sdwa v34, v44, v42 dst_sel:DWORD dst_unused:UNUSED_PAD src0_sel:DWORD src1_sel:WORD_1
	v_or_b32_sdwa v37, v47, v46 dst_sel:DWORD dst_unused:UNUSED_PAD src0_sel:DWORD src1_sel:WORD_1
	v_or_b32_sdwa v36, v48, v45 dst_sel:DWORD dst_unused:UNUSED_PAD src0_sel:DWORD src1_sel:WORD_1
	v_or_b32_sdwa v39, v51, v50 dst_sel:DWORD dst_unused:UNUSED_PAD src0_sel:DWORD src1_sel:WORD_1
	v_or_b32_sdwa v38, v52, v49 dst_sel:DWORD dst_unused:UNUSED_PAD src0_sel:DWORD src1_sel:WORD_1
	v_or_b32_sdwa v41, v64, v54 dst_sel:DWORD dst_unused:UNUSED_PAD src0_sel:DWORD src1_sel:WORD_1
	v_or_b32_sdwa v40, v65, v53 dst_sel:DWORD dst_unused:UNUSED_PAD src0_sel:DWORD src1_sel:WORD_1
	v_or_b32_sdwa v43, v67, v66 dst_sel:DWORD dst_unused:UNUSED_PAD src0_sel:DWORD src1_sel:WORD_1
	v_or_b32_sdwa v42, v68, v55 dst_sel:DWORD dst_unused:UNUSED_PAD src0_sel:DWORD src1_sel:WORD_1
	v_or_b32_sdwa v45, v69, v57 dst_sel:DWORD dst_unused:UNUSED_PAD src0_sel:DWORD src1_sel:WORD_1
	v_or_b32_sdwa v44, v70, v56 dst_sel:DWORD dst_unused:UNUSED_PAD src0_sel:DWORD src1_sel:WORD_1
	v_or_b32_sdwa v47, v60, v59 dst_sel:DWORD dst_unused:UNUSED_PAD src0_sel:DWORD src1_sel:WORD_1
	v_or_b32_sdwa v46, v61, v58 dst_sel:DWORD dst_unused:UNUSED_PAD src0_sel:DWORD src1_sel:WORD_1
	v_or_b32_sdwa v49, v71, v63 dst_sel:DWORD dst_unused:UNUSED_PAD src0_sel:DWORD src1_sel:WORD_1
	v_or_b32_sdwa v48, v72, v62 dst_sel:DWORD dst_unused:UNUSED_PAD src0_sel:DWORD src1_sel:WORD_1
	global_store_dwordx2 v[14:15], v[34:35], off
	global_store_dwordx2 v[14:15], v[36:37], off offset:512
	global_store_dwordx2 v[14:15], v[38:39], off offset:1024
	global_store_dwordx2 v[14:15], v[40:41], off offset:1536
	global_store_dwordx2 v[24:25], v[42:43], off
	global_store_dwordx2 v[24:25], v[44:45], off offset:512
	global_store_dwordx2 v[24:25], v[46:47], off offset:1024
	global_store_dwordx2 v[24:25], v[48:49], off offset:1536
	s_cbranch_scc0 .LBB0_99

.LBB0_1125:
	s_or_b64 exec, exec, s[30:31]
	s_and_b64 s[8:9], s[80:81], exec
	s_cselect_b32 s9, s13, s19
	s_cselect_b32 s8, s12, s18
	s_lshl_b64 s[12:13], s[90:91], 12
	s_add_u32 s12, s16, s12
	s_addc_u32 s13, s17, s13
	s_lshl_b32 s16, s25, 5
	s_lshl_b32 s17, s26, 8
	s_or_b32 s16, s17, s16
	v_lshrrev_b32_e32 v0, 2, v140
	v_add_u32_e32 v134, s27, v141
	v_and_or_b32 v0, v0, 12, s16
	v_ashrrev_i32_e32 v135, 31, v134
	v_ashrrev_i32_e32 v1, 31, v0
	v_lshlrev_b64 v[136:137], 10, v[134:135]
	s_waitcnt lgkmcnt(0)
	v_lshl_add_u32 v2, v141, 2, 0
	v_lshl_add_u64 v[140:141], v[136:137], 0, v[0:1]
	v_lshlrev_b64 v[146:147], 2, v[140:141]
	s_waitcnt lgkmcnt(0)
	s_barrier
	v_lshlrev_b32_e32 v144, 2, v0
	global_load_dwordx4 v[224:227], v144, s[12:13]
	global_load_dwordx2 v[196:197], v144, s[12:13] offset:64
	global_load_dwordx2 v[200:201], v144, s[12:13] offset:72
	global_load_dwordx2 v[228:229], v144, s[12:13] offset:512
	global_load_dwordx2 v[250:251], v144, s[12:13] offset:520
	global_load_dwordx2 v[254:255], v144, s[12:13] offset:576
	global_load_dwordx2 v[180:181], v144, s[12:13] offset:584
	global_load_dwordx4 v[136:139], v146, s[8:9] nt
	global_load_dwordx4 v[140:143], v146, s[8:9] offset:64 nt
	global_load_dwordx4 v[148:151], v146, s[8:9] offset:512 nt
	global_load_dwordx4 v[168:171], v146, s[8:9] offset:576 nt
	v_add_u32_e32 v198, 0x10000, v146
	global_load_dwordx4 v[172:175], v198, s[8:9] nt
	global_load_dwordx4 v[176:179], v198, s[8:9] offset:64 nt
	global_load_dwordx4 v[242:245], v198, s[8:9] offset:512 nt
	global_load_dwordx4 v[246:249], v198, s[8:9] offset:576 nt
	ds_read_b32 v190, v2 offset:8192
	ds_read_b32 v192, v2 offset:8256
	s_waitcnt lgkmcnt(1)
	v_pk_mul_f32 v[100:101], v[100:101], v[190:191] op_sel_hi:[1,0]
	v_pk_mul_f32 v[102:103], v[102:103], v[190:191] op_sel_hi:[1,0]
	v_pk_mul_f32 v[120:121], v[120:121], v[190:191] op_sel_hi:[1,0]
	v_pk_mul_f32 v[122:123], v[122:123], v[190:191] op_sel_hi:[1,0]
	v_pk_mul_f32 v[116:117], v[116:117], v[190:191] op_sel_hi:[1,0]
	v_pk_mul_f32 v[118:119], v[118:119], v[190:191] op_sel_hi:[1,0]
	v_pk_mul_f32 v[108:109], v[108:109], v[190:191] op_sel_hi:[1,0]
	v_pk_mul_f32 v[110:111], v[110:111], v[190:191] op_sel_hi:[1,0]
	s_waitcnt vmcnt(4)
	v_pk_fma_f32 v[100:101], v[224:225], v[100:101], v[136:137]
	v_pk_fma_f32 v[102:103], v[226:227], v[102:103], v[138:139]
	v_pk_fma_f32 v[120:121], v[196:197], v[120:121], v[140:141]
	v_pk_fma_f32 v[122:123], v[200:201], v[122:123], v[142:143]
	v_pk_fma_f32 v[116:117], v[228:229], v[116:117], v[148:149]
	v_pk_fma_f32 v[118:119], v[250:251], v[118:119], v[150:151]
	v_pk_fma_f32 v[108:109], v[254:255], v[108:109], v[168:169]
	v_pk_fma_f32 v[110:111], v[180:181], v[110:111], v[170:171]
	global_store_dwordx4 v146, v[100:103], s[18:19] nt
	global_store_dwordx4 v146, v[120:123], s[18:19] offset:64 nt
	global_store_dwordx4 v146, v[116:119], s[18:19] offset:512 nt
	global_store_dwordx4 v146, v[108:111], s[18:19] offset:576 nt
	v_add_u32_e32 v198, 0x20000, v146
	global_load_dwordx4 v[136:139], v198, s[8:9] nt
	global_load_dwordx4 v[140:143], v198, s[8:9] offset:64 nt
	global_load_dwordx4 v[148:151], v198, s[8:9] offset:512 nt
	global_load_dwordx4 v[168:171], v198, s[8:9] offset:576 nt
	ds_read_b32 v190, v2 offset:8320
	s_waitcnt lgkmcnt(1)
	v_pk_mul_f32 v[128:129], v[128:129], v[192:193] op_sel_hi:[1,0]
	v_pk_mul_f32 v[130:131], v[130:131], v[192:193] op_sel_hi:[1,0]
	v_pk_mul_f32 v[124:125], v[124:125], v[192:193] op_sel_hi:[1,0]
	v_pk_mul_f32 v[126:127], v[126:127], v[192:193] op_sel_hi:[1,0]
	v_pk_mul_f32 v[112:113], v[112:113], v[192:193] op_sel_hi:[1,0]
	v_pk_mul_f32 v[114:115], v[114:115], v[192:193] op_sel_hi:[1,0]
	v_pk_mul_f32 v[104:105], v[104:105], v[192:193] op_sel_hi:[1,0]
	v_pk_mul_f32 v[106:107], v[106:107], v[192:193] op_sel_hi:[1,0]
	s_waitcnt vmcnt(8)
	v_pk_fma_f32 v[128:129], v[224:225], v[128:129], v[172:173]
	v_pk_fma_f32 v[130:131], v[226:227], v[130:131], v[174:175]
	v_pk_fma_f32 v[124:125], v[196:197], v[124:125], v[176:177]
	v_pk_fma_f32 v[126:127], v[200:201], v[126:127], v[178:179]
	v_pk_fma_f32 v[112:113], v[228:229], v[112:113], v[242:243]
	v_pk_fma_f32 v[114:115], v[250:251], v[114:115], v[244:245]
	v_pk_fma_f32 v[104:105], v[254:255], v[104:105], v[246:247]
	v_pk_fma_f32 v[106:107], v[180:181], v[106:107], v[248:249]
	v_add_u32_e32 v145, 0x10000, v146
	global_store_dwordx4 v145, v[128:131], s[18:19] nt
	global_store_dwordx4 v145, v[124:127], s[18:19] offset:64 nt
	global_store_dwordx4 v145, v[112:115], s[18:19] offset:512 nt
	global_store_dwordx4 v145, v[104:107], s[18:19] offset:576 nt
	v_add_u32_e32 v198, 0x30000, v146
	global_load_dwordx4 v[172:175], v198, s[8:9] nt
	global_load_dwordx4 v[176:179], v198, s[8:9] offset:64 nt
	global_load_dwordx4 v[242:245], v198, s[8:9] offset:512 nt
	global_load_dwordx4 v[246:249], v198, s[8:9] offset:576 nt
	ds_read_b32 v192, v2 offset:8384
	s_waitcnt lgkmcnt(1)
	v_pk_mul_f32 v[96:97], v[96:97], v[190:191] op_sel_hi:[1,0]
	v_pk_mul_f32 v[98:99], v[98:99], v[190:191] op_sel_hi:[1,0]
	v_pk_mul_f32 v[92:93], v[92:93], v[190:191] op_sel_hi:[1,0]
	v_pk_mul_f32 v[94:95], v[94:95], v[190:191] op_sel_hi:[1,0]
	v_pk_mul_f32 v[88:89], v[88:89], v[190:191] op_sel_hi:[1,0]
	v_pk_mul_f32 v[90:91], v[90:91], v[190:191] op_sel_hi:[1,0]
	v_pk_mul_f32 v[84:85], v[84:85], v[190:191] op_sel_hi:[1,0]
	v_pk_mul_f32 v[86:87], v[86:87], v[190:191] op_sel_hi:[1,0]
	s_waitcnt vmcnt(8)
	v_pk_fma_f32 v[96:97], v[224:225], v[96:97], v[136:137]
	v_pk_fma_f32 v[98:99], v[226:227], v[98:99], v[138:139]
	v_pk_fma_f32 v[92:93], v[196:197], v[92:93], v[140:141]
	v_pk_fma_f32 v[94:95], v[200:201], v[94:95], v[142:143]
	v_pk_fma_f32 v[88:89], v[228:229], v[88:89], v[148:149]
	v_pk_fma_f32 v[90:91], v[250:251], v[90:91], v[150:151]
	v_pk_fma_f32 v[84:85], v[254:255], v[84:85], v[168:169]
	v_pk_fma_f32 v[86:87], v[180:181], v[86:87], v[170:171]
	v_add_u32_e32 v145, 0x20000, v146
	global_store_dwordx4 v145, v[96:99], s[18:19] nt
	global_store_dwordx4 v145, v[92:95], s[18:19] offset:64 nt
	global_store_dwordx4 v145, v[88:91], s[18:19] offset:512 nt
	global_store_dwordx4 v145, v[84:87], s[18:19] offset:576 nt
	v_add_u32_e32 v198, 0x80000, v146
	global_load_dwordx4 v[136:139], v198, s[8:9] nt
	global_load_dwordx4 v[140:143], v198, s[8:9] offset:64 nt
	global_load_dwordx4 v[148:151], v198, s[8:9] offset:512 nt
	global_load_dwordx4 v[168:171], v198, s[8:9] offset:576 nt
	ds_read_b32 v190, v2 offset:8704
	s_waitcnt lgkmcnt(1)
	v_pk_mul_f32 v[80:81], v[80:81], v[192:193] op_sel_hi:[1,0]
	v_pk_mul_f32 v[82:83], v[82:83], v[192:193] op_sel_hi:[1,0]
	v_pk_mul_f32 v[76:77], v[76:77], v[192:193] op_sel_hi:[1,0]
	v_pk_mul_f32 v[78:79], v[78:79], v[192:193] op_sel_hi:[1,0]
	v_pk_mul_f32 v[72:73], v[72:73], v[192:193] op_sel_hi:[1,0]
	v_pk_mul_f32 v[74:75], v[74:75], v[192:193] op_sel_hi:[1,0]
	v_pk_mul_f32 v[68:69], v[68:69], v[192:193] op_sel_hi:[1,0]
	v_pk_mul_f32 v[70:71], v[70:71], v[192:193] op_sel_hi:[1,0]
	s_waitcnt vmcnt(8)
	v_pk_fma_f32 v[80:81], v[224:225], v[80:81], v[172:173]
	v_pk_fma_f32 v[82:83], v[226:227], v[82:83], v[174:175]
	v_pk_fma_f32 v[76:77], v[196:197], v[76:77], v[176:177]
	v_pk_fma_f32 v[78:79], v[200:201], v[78:79], v[178:179]
	v_pk_fma_f32 v[72:73], v[228:229], v[72:73], v[242:243]
	v_pk_fma_f32 v[74:75], v[250:251], v[74:75], v[244:245]
	v_pk_fma_f32 v[68:69], v[254:255], v[68:69], v[246:247]
	v_pk_fma_f32 v[70:71], v[180:181], v[70:71], v[248:249]
	v_add_u32_e32 v145, 0x30000, v146
	global_store_dwordx4 v145, v[80:83], s[18:19] nt
	global_store_dwordx4 v145, v[76:79], s[18:19] offset:64 nt
	global_store_dwordx4 v145, v[72:75], s[18:19] offset:512 nt
	global_store_dwordx4 v145, v[68:71], s[18:19] offset:576 nt
	v_add_u32_e32 v198, 0x90000, v146
	global_load_dwordx4 v[172:175], v198, s[8:9] nt
	global_load_dwordx4 v[176:179], v198, s[8:9] offset:64 nt
	global_load_dwordx4 v[242:245], v198, s[8:9] offset:512 nt
	global_load_dwordx4 v[246:249], v198, s[8:9] offset:576 nt
	ds_read_b32 v192, v2 offset:8768
	s_waitcnt lgkmcnt(1)
	v_pk_mul_f32 v[64:65], v[64:65], v[190:191] op_sel_hi:[1,0]
	v_pk_mul_f32 v[66:67], v[66:67], v[190:191] op_sel_hi:[1,0]
	v_pk_mul_f32 v[60:61], v[60:61], v[190:191] op_sel_hi:[1,0]
	v_pk_mul_f32 v[62:63], v[62:63], v[190:191] op_sel_hi:[1,0]
	v_pk_mul_f32 v[56:57], v[56:57], v[190:191] op_sel_hi:[1,0]
	v_pk_mul_f32 v[58:59], v[58:59], v[190:191] op_sel_hi:[1,0]
	v_pk_mul_f32 v[52:53], v[52:53], v[190:191] op_sel_hi:[1,0]
	v_pk_mul_f32 v[54:55], v[54:55], v[190:191] op_sel_hi:[1,0]
	s_waitcnt vmcnt(8)
	v_pk_fma_f32 v[64:65], v[224:225], v[64:65], v[136:137]
	v_pk_fma_f32 v[66:67], v[226:227], v[66:67], v[138:139]
	v_pk_fma_f32 v[60:61], v[196:197], v[60:61], v[140:141]
	v_pk_fma_f32 v[62:63], v[200:201], v[62:63], v[142:143]
	v_pk_fma_f32 v[56:57], v[228:229], v[56:57], v[148:149]
	v_pk_fma_f32 v[58:59], v[250:251], v[58:59], v[150:151]
	v_pk_fma_f32 v[52:53], v[254:255], v[52:53], v[168:169]
	v_pk_fma_f32 v[54:55], v[180:181], v[54:55], v[170:171]
	v_add_u32_e32 v145, 0x80000, v146
	global_store_dwordx4 v145, v[64:67], s[18:19] nt
	global_store_dwordx4 v145, v[60:63], s[18:19] offset:64 nt
	global_store_dwordx4 v145, v[56:59], s[18:19] offset:512 nt
	global_store_dwordx4 v145, v[52:55], s[18:19] offset:576 nt
	v_add_u32_e32 v198, 0xa0000, v146
	global_load_dwordx4 v[136:139], v198, s[8:9] nt
	global_load_dwordx4 v[140:143], v198, s[8:9] offset:64 nt
	global_load_dwordx4 v[148:151], v198, s[8:9] offset:512 nt
	global_load_dwordx4 v[168:171], v198, s[8:9] offset:576 nt
	ds_read_b32 v190, v2 offset:8832
	s_waitcnt lgkmcnt(1)
	v_pk_mul_f32 v[48:49], v[48:49], v[192:193] op_sel_hi:[1,0]
	v_pk_mul_f32 v[50:51], v[50:51], v[192:193] op_sel_hi:[1,0]
	v_pk_mul_f32 v[44:45], v[44:45], v[192:193] op_sel_hi:[1,0]
	v_pk_mul_f32 v[46:47], v[46:47], v[192:193] op_sel_hi:[1,0]
	v_pk_mul_f32 v[40:41], v[40:41], v[192:193] op_sel_hi:[1,0]
	v_pk_mul_f32 v[42:43], v[42:43], v[192:193] op_sel_hi:[1,0]
	v_pk_mul_f32 v[36:37], v[36:37], v[192:193] op_sel_hi:[1,0]
	v_pk_mul_f32 v[38:39], v[38:39], v[192:193] op_sel_hi:[1,0]
	s_waitcnt vmcnt(8)
	v_pk_fma_f32 v[48:49], v[224:225], v[48:49], v[172:173]
	v_pk_fma_f32 v[50:51], v[226:227], v[50:51], v[174:175]
	v_pk_fma_f32 v[44:45], v[196:197], v[44:45], v[176:177]
	v_pk_fma_f32 v[46:47], v[200:201], v[46:47], v[178:179]
	v_pk_fma_f32 v[40:41], v[228:229], v[40:41], v[242:243]
	v_pk_fma_f32 v[42:43], v[250:251], v[42:43], v[244:245]
	v_pk_fma_f32 v[36:37], v[254:255], v[36:37], v[246:247]
	v_pk_fma_f32 v[38:39], v[180:181], v[38:39], v[248:249]
	v_add_u32_e32 v145, 0x90000, v146
	global_store_dwordx4 v145, v[48:51], s[18:19] nt
	global_store_dwordx4 v145, v[44:47], s[18:19] offset:64 nt
	global_store_dwordx4 v145, v[40:43], s[18:19] offset:512 nt
	global_store_dwordx4 v145, v[36:39], s[18:19] offset:576 nt
	v_add_u32_e32 v198, 0xb0000, v146
	global_load_dwordx4 v[172:175], v198, s[8:9] nt
	global_load_dwordx4 v[176:179], v198, s[8:9] offset:64 nt
	global_load_dwordx4 v[242:245], v198, s[8:9] offset:512 nt
	global_load_dwordx4 v[246:249], v198, s[8:9] offset:576 nt
	ds_read_b32 v192, v2 offset:8896
	s_waitcnt lgkmcnt(1)
	v_pk_mul_f32 v[32:33], v[32:33], v[190:191] op_sel_hi:[1,0]
	v_pk_mul_f32 v[34:35], v[34:35], v[190:191] op_sel_hi:[1,0]
	v_pk_mul_f32 v[28:29], v[28:29], v[190:191] op_sel_hi:[1,0]
	v_pk_mul_f32 v[30:31], v[30:31], v[190:191] op_sel_hi:[1,0]
	v_pk_mul_f32 v[24:25], v[24:25], v[190:191] op_sel_hi:[1,0]
	v_pk_mul_f32 v[26:27], v[26:27], v[190:191] op_sel_hi:[1,0]
	v_pk_mul_f32 v[20:21], v[20:21], v[190:191] op_sel_hi:[1,0]
	v_pk_mul_f32 v[22:23], v[22:23], v[190:191] op_sel_hi:[1,0]
	s_waitcnt vmcnt(8)
	v_pk_fma_f32 v[32:33], v[224:225], v[32:33], v[136:137]
	v_pk_fma_f32 v[34:35], v[226:227], v[34:35], v[138:139]
	v_pk_fma_f32 v[28:29], v[196:197], v[28:29], v[140:141]
	v_pk_fma_f32 v[30:31], v[200:201], v[30:31], v[142:143]
	v_pk_fma_f32 v[24:25], v[228:229], v[24:25], v[148:149]
	v_pk_fma_f32 v[26:27], v[250:251], v[26:27], v[150:151]
	v_pk_fma_f32 v[20:21], v[254:255], v[20:21], v[168:169]
	v_pk_fma_f32 v[22:23], v[180:181], v[22:23], v[170:171]
	v_add_u32_e32 v145, 0xa0000, v146
	global_store_dwordx4 v145, v[32:35], s[18:19] nt
	global_store_dwordx4 v145, v[28:31], s[18:19] offset:64 nt
	global_store_dwordx4 v145, v[24:27], s[18:19] offset:512 nt
	global_store_dwordx4 v145, v[20:23], s[18:19] offset:576 nt
	s_waitcnt lgkmcnt(0)
	v_pk_mul_f32 v[16:17], v[16:17], v[192:193] op_sel_hi:[1,0]
	v_pk_mul_f32 v[18:19], v[18:19], v[192:193] op_sel_hi:[1,0]
	v_pk_mul_f32 v[12:13], v[12:13], v[192:193] op_sel_hi:[1,0]
	v_pk_mul_f32 v[14:15], v[14:15], v[192:193] op_sel_hi:[1,0]
	v_pk_mul_f32 v[8:9], v[8:9], v[192:193] op_sel_hi:[1,0]
	v_pk_mul_f32 v[10:11], v[10:11], v[192:193] op_sel_hi:[1,0]
	v_pk_mul_f32 v[4:5], v[4:5], v[192:193] op_sel_hi:[1,0]
	v_pk_mul_f32 v[6:7], v[6:7], v[192:193] op_sel_hi:[1,0]
	s_waitcnt vmcnt(4)
	v_pk_fma_f32 v[16:17], v[224:225], v[16:17], v[172:173]
	v_pk_fma_f32 v[18:19], v[226:227], v[18:19], v[174:175]
	v_pk_fma_f32 v[12:13], v[196:197], v[12:13], v[176:177]
	v_pk_fma_f32 v[14:15], v[200:201], v[14:15], v[178:179]
	v_pk_fma_f32 v[8:9], v[228:229], v[8:9], v[242:243]
	v_pk_fma_f32 v[10:11], v[250:251], v[10:11], v[244:245]
	v_pk_fma_f32 v[4:5], v[254:255], v[4:5], v[246:247]
	v_pk_fma_f32 v[6:7], v[180:181], v[6:7], v[248:249]
	v_add_u32_e32 v145, 0xb0000, v146
	global_store_dwordx4 v145, v[16:19], s[18:19] nt
	global_store_dwordx4 v145, v[12:15], s[18:19] offset:64 nt
	global_store_dwordx4 v145, v[8:11], s[18:19] offset:512 nt
	global_store_dwordx4 v145, v[4:7], s[18:19] offset:576 nt
	s_mov_b64 s[8:9], 0
	s_andn2_b64 vcc, exec, s[80:81]
	s_nop 1
	s_cbranch_vccnz .LBB0_1162
	v_mul_f32_e32 v150, v101, v101
	v_mul_f32_e32 v151, v103, v103
	v_fmac_f32_e32 v150, v100, v100
	v_fmac_f32_e32 v151, v102, v102
	v_add_f32_e32 v150, v150, v151
	v_mul_f32_e32 v151, v121, v121
	v_mul_f32_e32 v161, v123, v123
	v_fmac_f32_e32 v151, v120, v120
	v_fmac_f32_e32 v161, v122, v122
	v_add_f32_e32 v151, v151, v161
	v_add_f32_e32 v150, v150, v151
	v_mul_f32_e32 v151, v117, v117
	v_mul_f32_e32 v161, v119, v119
	v_fmac_f32_e32 v151, v116, v116
	v_fmac_f32_e32 v161, v118, v118
	v_add_f32_e32 v151, v151, v161
	v_add_f32_e32 v150, v151, v150
	v_mul_f32_e32 v151, v109, v109
	v_mul_f32_e32 v161, v111, v111
	v_fmac_f32_e32 v151, v108, v108
	v_fmac_f32_e32 v161, v110, v110
	v_add_f32_e32 v151, v151, v161
	v_add_f32_e32 v150, v151, v150
	ds_bpermute_b32 v151, v153, v150
	s_waitcnt lgkmcnt(0)
	v_add_f32_e32 v150, v150, v151
	ds_bpermute_b32 v151, v154, v150
	s_and_saveexec_b64 s[8:9], s[2:3]
	s_cbranch_execz .LBB0_1128
	s_lshl_b32 s12, s0, 10
	s_add_i32 s12, s1, s12
	v_lshl_add_u32 v161, v152, 4, s12
	s_waitcnt lgkmcnt(0)
	v_add_f32_e32 v150, v150, v151
	ds_write_b32 v161, v150
